# LN-mix router logits: four experts interleaved (dependent packed FMAs four instructions apart), 11 LDS reads in flight, half the lgkmcnt waits
# baseline (speedup 1.0000x reference)
.LBB0_684:
	s_or_b64 exec, exec, s[24:25]
	v_lshlrev_b32_e32 v164, 16, v142
	v_and_b32_e32 v165, 0xffff0000, v142
	v_lshlrev_b32_e32 v162, 16, v144
	v_and_b32_e32 v163, 0xffff0000, v144
	v_pk_mul_f32 v[164:165], v[36:37], v[164:165]
	v_lshlrev_b32_e32 v142, 16, v143
	v_and_b32_e32 v143, 0xffff0000, v143
	v_pk_mul_f32 v[162:163], v[52:53], v[162:163]
	v_pk_fma_f32 v[104:105], v[104:105], s[22:23], v[164:165] op_sel_hi:[1,0,1]
	v_pk_mul_f32 v[142:143], v[38:39], v[142:143]
	v_pk_fma_f32 v[108:109], v[108:109], s[22:23], v[162:163] op_sel_hi:[1,0,1]
	v_and_b32_e32 v163, 0xffff0000, v145
	v_lshlrev_b32_e32 v162, 16, v145
	v_lshlrev_b32_e32 v127, 16, v138
	v_mov_b32_e32 v101, v64
	v_and_b32_e32 v96, 0xffff0000, v140
	v_pk_add_f32 v[164:165], v[104:105], v[104:105] op_sel:[0,1] op_sel_hi:[1,0]
	v_pk_fma_f32 v[106:107], v[106:107], s[22:23], v[142:143] op_sel_hi:[1,0,1]
	v_pk_mul_f32 v[144:145], v[54:55], v[162:163]
	v_pk_mul_f32 v[100:101], v[100:101], v[126:127]
	v_and_b32_e32 v127, 0xffff0000, v138
	v_mul_f32_e32 v163, v77, v96
	v_and_b32_e32 v96, 0xffff0000, v141
	v_pk_add_f32 v[142:143], v[106:107], v[164:165]
	v_lshlrev_b32_e32 v165, 16, v140
	v_lshlrev_b32_e32 v164, 16, v139
	v_and_b32_e32 v138, 0xffff0000, v139
	v_lshlrev_b32_e32 v139, 16, v141
	v_pk_mov_b32 v[140:141], v[66:67], v[78:79] op_sel:[1,0]
	v_pk_fma_f32 v[110:111], v[110:111], s[22:23], v[144:145] op_sel_hi:[1,0,1]
	v_pk_mul_f32 v[138:139], v[140:141], v[138:139]
	v_pk_add_f32 v[140:141], v[106:107], v[142:143] op_sel:[1,0] op_sel_hi:[0,1]
	v_pk_add_f32 v[144:145], v[108:109], v[108:109] op_sel:[0,1] op_sel_hi:[1,0]
	s_waitcnt lgkmcnt(0)
	v_mov_b32_e32 v98, v140
	v_pk_add_f32 v[144:145], v[110:111], v[144:145]
	v_pk_add_f32 v[140:141], v[140:141], s[18:19]
	v_pk_mul_f32 v[98:99], v[98:99], s[0:1]
	v_mov_b32_e32 v149, v65
	v_mul_f32_e32 v96, v79, v96
	v_mov_b32_e32 v141, v99
	v_pk_add_f32 v[98:99], v[110:111], v[144:145] op_sel:[1,0] op_sel_hi:[0,1]
	v_pk_mul_f32 v[148:149], v[148:149], v[126:127]
	v_mov_b32_e32 v99, v96
	v_pk_add_f32 v[98:99], v[140:141], v[98:99]
	v_mov_b32_e32 v140, v100
	v_mov_b32_e32 v141, v148
	v_mov_b32_e32 v148, v101
	v_mov_b32_e32 v166, v66
	v_mov_b32_e32 v167, v76
	v_pk_add_f32 v[100:101], v[140:141], v[148:149]
	v_mul_f32_e32 v97, 0x3fb504f3, v97
	v_pk_mul_f32 v[164:165], v[166:167], v[164:165]
	v_mov_b32_e32 v96, v100
	v_mov_b32_e32 v162, v101
	v_pk_fma_f32 v[102:103], v[102:103], s[22:23], v[164:165] op_sel_hi:[1,0,1]
	v_pk_add_f32 v[96:97], v[96:97], v[162:163]
	v_pk_fma_f32 v[138:139], v[146:147], s[22:23], v[138:139] op_sel_hi:[1,0,1]
	v_pk_add_f32 v[140:141], v[102:103], v[96:97]
	v_mov_b32_e32 v164, v102
	v_pk_add_f32 v[140:141], v[138:139], v[140:141]
	v_mov_b32_e32 v165, v138
	v_pk_add_f32 v[140:141], v[98:99], v[140:141]
	v_ashrrev_i32_e32 v115, 31, v114
	v_add_f32_e32 v96, v140, v141
	ds_bpermute_b32 v98, v150, v96
	s_waitcnt lgkmcnt(0)
	v_add_f32_e32 v96, v96, v98
	ds_bpermute_b32 v98, v151, v96
	s_waitcnt lgkmcnt(0)
	v_add_f32_e32 v96, v96, v98
	ds_bpermute_b32 v98, v152, v96
	s_waitcnt lgkmcnt(0)
	v_add_f32_e32 v96, v96, v98
	ds_bpermute_b32 v98, v153, v96
	s_waitcnt lgkmcnt(0)
	v_add_f32_e32 v96, v96, v98
	ds_bpermute_b32 v98, v154, v96
	s_waitcnt lgkmcnt(0)
	v_add_f32_e32 v96, v96, v98
	ds_bpermute_b32 v98, v155, v96
	s_waitcnt lgkmcnt(0)
	v_add_f32_e32 v96, v96, v98
	v_mul_f32_e32 v140, 0x3a800000, v96
	v_pk_add_f32 v[104:105], v[104:105], v[140:141] op_sel_hi:[1,0] neg_lo:[0,1] neg_hi:[0,1]
	v_pk_add_f32 v[106:107], v[106:107], v[140:141] op_sel_hi:[1,0] neg_lo:[0,1] neg_hi:[0,1]
	v_pk_mul_f32 v[142:143], v[104:105], v[104:105]
	v_pk_mul_f32 v[144:145], v[106:107], v[106:107]
	v_add_f32_e32 v102, v142, v143
	v_pk_add_f32 v[108:109], v[108:109], v[140:141] op_sel_hi:[1,0] neg_lo:[0,1] neg_hi:[0,1]
	v_add_f32_e32 v102, v144, v102
	v_pk_mul_f32 v[148:149], v[108:109], v[108:109]
	v_add_f32_e32 v102, v145, v102
	v_pk_add_f32 v[110:111], v[110:111], v[140:141] op_sel_hi:[1,0] neg_lo:[0,1] neg_hi:[0,1]
	v_add_f32_e32 v102, v148, v102
	v_pk_mul_f32 v[162:163], v[110:111], v[110:111]
	v_add_f32_e32 v102, v149, v102
	v_pk_add_f32 v[146:147], v[100:101], v[140:141] op_sel_hi:[1,0] neg_lo:[0,1] neg_hi:[0,1]
	v_add_f32_e32 v102, v162, v102
	v_pk_mul_f32 v[100:101], v[146:147], v[146:147]
	v_add_f32_e32 v102, v163, v102
	v_pk_add_f32 v[164:165], v[164:165], v[140:141] op_sel_hi:[1,0] neg_lo:[0,1] neg_hi:[0,1]
	v_add_f32_e32 v100, v100, v102
	v_pk_mul_f32 v[166:167], v[164:165], v[164:165]
	v_mov_b32_e32 v96, v103
	v_add_f32_e32 v100, v101, v100
	v_pk_add_f32 v[168:169], v[96:97], v[140:141] op_sel_hi:[1,0] neg_lo:[0,1] neg_hi:[0,1]
	v_add_f32_e32 v100, v166, v100
	v_pk_mul_f32 v[96:97], v[168:169], v[168:169]
	v_mov_b32_e32 v98, v139
	v_add_f32_e32 v100, v167, v100
	v_pk_add_f32 v[138:139], v[98:99], v[140:141] op_sel_hi:[1,0] neg_lo:[0,1] neg_hi:[0,1]
	v_add_f32_e32 v96, v96, v100
	v_pk_mul_f32 v[98:99], v[138:139], v[138:139]
	v_add_f32_e32 v96, v97, v96
	v_add_f32_e32 v96, v98, v96
	v_add_f32_e32 v96, v99, v96
	ds_bpermute_b32 v97, v150, v96
	v_pk_add_f32 v[102:103], v[34:35], 1.0 op_sel_hi:[1,0]
	v_pk_add_f32 v[144:145], v[40:41], 1.0 op_sel_hi:[1,0]
	v_pk_add_f32 v[148:149], v[42:43], 1.0 op_sel_hi:[1,0]
	v_pk_add_f32 v[162:163], v[56:57], 1.0 op_sel_hi:[1,0]
	s_waitcnt lgkmcnt(0)
	v_add_f32_e32 v96, v96, v97
	ds_bpermute_b32 v97, v151, v96
	v_pk_add_f32 v[166:167], v[58:59], 1.0 op_sel_hi:[1,0]
	s_waitcnt lgkmcnt(0)
	v_add_f32_e32 v96, v96, v97
	ds_bpermute_b32 v97, v152, v96
	s_waitcnt lgkmcnt(0)
	v_add_f32_e32 v96, v96, v97
	ds_bpermute_b32 v97, v153, v96
	s_waitcnt lgkmcnt(0)
	v_add_f32_e32 v98, v96, v97
	ds_bpermute_b32 v99, v154, v98
	v_lshlrev_b64 v[96:97], 12, v[114:115]
	v_lshl_add_u64 v[140:141], v[122:123], 0, v[96:97]
	v_pk_add_f32 v[96:97], v[32:33], 1.0 op_sel_hi:[1,0]
	s_waitcnt lgkmcnt(0)
	v_add_f32_e32 v100, v98, v99
	ds_bpermute_b32 v101, v155, v100
	v_lshlrev_b64 v[98:99], 11, v[114:115]
	v_lshl_add_u64 v[142:143], v[124:125], 0, v[98:99]
	s_waitcnt lgkmcnt(0)
	v_add_f32_e32 v98, v100, v101
	v_fmamk_f32 v98, v98, 0x3a800000, v159
	v_mul_f32_e32 v99, 0x4b800000, v98
	v_cmp_gt_f32_e32 vcc, s19, v98
	s_nop 1
	v_cndmask_b32_e32 v98, v98, v99, vcc
	v_rsq_f32_e32 v98, v98
	s_nop 0
	v_mul_f32_e32 v99, 0x45800000, v98
	v_cndmask_b32_e32 v170, v98, v99, vcc
	v_pk_mul_f32 v[98:99], v[104:105], v[170:171] op_sel_hi:[1,0]
	v_pk_mul_f32 v[100:101], v[106:107], v[170:171] op_sel_hi:[1,0]
	v_pk_fma_f32 v[98:99], v[28:29], v[98:99], v[24:25]
	v_pk_fma_f32 v[100:101], v[30:31], v[100:101], v[26:27]
	global_store_dwordx4 v[140:141], v[98:101], off sc1 nt
	s_nop 1
	v_pk_fma_f32 v[98:99], v[96:97], v[98:99], v[44:45]
	v_pk_fma_f32 v[96:97], v[102:103], v[100:101], v[46:47]
	v_cvt_pk_bf16_f32 v100, v98, v99
	v_cvt_pk_bf16_f32 v101, v96, v97
	global_store_dwordx2 v[142:143], v[100:101], off
	v_pk_mul_f32 v[100:101], v[108:109], v[170:171] op_sel_hi:[1,0]
	s_nop 0
	v_pk_fma_f32 v[102:103], v[20:21], v[100:101], v[16:17]
	v_pk_mul_f32 v[100:101], v[110:111], v[170:171] op_sel_hi:[1,0]
	v_pk_mul_f32 v[110:111], v[138:139], v[170:171] op_sel_hi:[1,0]
	v_pk_fma_f32 v[104:105], v[22:23], v[100:101], v[18:19]
	global_store_dwordx4 v[140:141], v[102:105], off offset:1024 sc1 nt
	v_pk_fma_f32 v[100:101], v[148:149], v[104:105], v[50:51]
	v_pk_fma_f32 v[110:111], v[6:7], v[110:111], v[2:3]
	v_pk_fma_f32 v[102:103], v[144:145], v[102:103], v[48:49]
	v_cvt_pk_bf16_f32 v105, v100, v101
	v_cvt_pk_bf16_f32 v104, v102, v103
	global_store_dwordx2 v[142:143], v[104:105], off offset:512
	v_pk_mul_f32 v[104:105], v[146:147], v[170:171] op_sel_hi:[1,0]
	v_pk_add_f32 v[138:139], v[68:69], 1.0 op_sel_hi:[1,0]
	v_pk_fma_f32 v[106:107], v[12:13], v[104:105], v[8:9]
	v_pk_mul_f32 v[104:105], v[164:165], v[170:171] op_sel_hi:[1,0]
	s_nop 0
	v_pk_fma_f32 v[108:109], v[14:15], v[104:105], v[10:11]
	global_store_dwordx4 v[140:141], v[106:109], off offset:2048 sc1 nt
	v_pk_fma_f32 v[104:105], v[166:167], v[108:109], v[62:63]
	s_nop 0
	v_pk_fma_f32 v[106:107], v[162:163], v[106:107], v[60:61]
	v_cvt_pk_bf16_f32 v109, v104, v105
	v_cvt_pk_bf16_f32 v108, v106, v107
	global_store_dwordx2 v[142:143], v[108:109], off offset:1024
	v_pk_mul_f32 v[108:109], v[168:169], v[170:171] op_sel_hi:[1,0]
	s_nop 0
	v_pk_fma_f32 v[108:109], v[4:5], v[108:109], v[0:1]
	global_store_dwordx4 v[140:141], v[108:111], off offset:3072 sc1 nt
	s_nop 1
	v_pk_fma_f32 v[108:109], v[138:139], v[108:109], v[72:73]
	v_pk_add_f32 v[138:139], v[70:71], 1.0 op_sel_hi:[1,0]
	v_cvt_pk_bf16_f32 v144, v108, v109
	v_pk_fma_f32 v[110:111], v[138:139], v[110:111], v[74:75]
	v_cvt_pk_bf16_f32 v145, v110, v111
	global_store_dwordx2 v[142:143], v[144:145], off offset:1536
	ds_read_b128 v[216:219], v156
	ds_read_b128 v[220:223], v156 offset:4096
	ds_read_b128 v[224:227], v156 offset:8192
	ds_read_b128 v[228:231], v156 offset:12288
	ds_read_b128 v[232:235], v156 offset:1024
	ds_read_b128 v[236:239], v156 offset:5120
	ds_read_b128 v[240:243], v156 offset:9216
	ds_read_b128 v[244:247], v156 offset:13312
	ds_read_b128 v[248:251], v156 offset:2048
	ds_read_b128 v[192:195], v156 offset:6144
	ds_read_b128 v[196:199], v156 offset:10240
	s_waitcnt lgkmcnt(7)
	v_pk_mul_f32 v[200:201], v[98:99], v[216:217]
	v_pk_mul_f32 v[202:203], v[98:99], v[220:221]
	v_pk_mul_f32 v[204:205], v[98:99], v[224:225]
	v_pk_mul_f32 v[206:207], v[98:99], v[228:229]
	v_pk_fma_f32 v[200:201], v[96:97], v[218:219], v[200:201]
	v_pk_fma_f32 v[202:203], v[96:97], v[222:223], v[202:203]
	v_pk_fma_f32 v[204:205], v[96:97], v[226:227], v[204:205]
	v_pk_fma_f32 v[206:207], v[96:97], v[230:231], v[206:207]
	ds_read_b128 v[216:219], v156 offset:14336
	ds_read_b128 v[220:223], v156 offset:3072
	ds_read_b128 v[224:227], v156 offset:7168
	ds_read_b128 v[228:231], v156 offset:11264
	s_waitcnt lgkmcnt(7)
	v_pk_fma_f32 v[200:201], v[102:103], v[232:233], v[200:201]
	v_pk_fma_f32 v[202:203], v[102:103], v[236:237], v[202:203]
	v_pk_fma_f32 v[204:205], v[102:103], v[240:241], v[204:205]
	v_pk_fma_f32 v[206:207], v[102:103], v[244:245], v[206:207]
	v_pk_fma_f32 v[200:201], v[100:101], v[234:235], v[200:201]
	v_pk_fma_f32 v[202:203], v[100:101], v[238:239], v[202:203]
	v_pk_fma_f32 v[204:205], v[100:101], v[242:243], v[204:205]
	v_pk_fma_f32 v[206:207], v[100:101], v[246:247], v[206:207]
	ds_read_b128 v[232:235], v156 offset:15360
	ds_read_b128 v[236:239], v156 offset:16384
	ds_read_b128 v[240:243], v156 offset:20480
	ds_read_b128 v[244:247], v156 offset:24576
	s_waitcnt lgkmcnt(7)
	v_pk_fma_f32 v[200:201], v[106:107], v[248:249], v[200:201]
	v_pk_fma_f32 v[202:203], v[106:107], v[192:193], v[202:203]
	v_pk_fma_f32 v[204:205], v[106:107], v[196:197], v[204:205]
	v_pk_fma_f32 v[206:207], v[106:107], v[216:217], v[206:207]
	v_pk_fma_f32 v[200:201], v[104:105], v[250:251], v[200:201]
	v_pk_fma_f32 v[202:203], v[104:105], v[194:195], v[202:203]
	v_pk_fma_f32 v[204:205], v[104:105], v[198:199], v[204:205]
	v_pk_fma_f32 v[206:207], v[104:105], v[218:219], v[206:207]
	ds_read_b128 v[248:251], v156 offset:28672
	ds_read_b128 v[192:195], v156 offset:17408
	ds_read_b128 v[196:199], v156 offset:21504
	ds_read_b128 v[216:219], v156 offset:25600
	s_waitcnt lgkmcnt(7)
	v_pk_fma_f32 v[200:201], v[108:109], v[220:221], v[200:201]
	v_pk_fma_f32 v[202:203], v[108:109], v[224:225], v[202:203]
	v_pk_fma_f32 v[204:205], v[108:109], v[228:229], v[204:205]
	v_pk_fma_f32 v[206:207], v[108:109], v[232:233], v[206:207]
	v_pk_fma_f32 v[200:201], v[110:111], v[222:223], v[200:201]
	v_pk_fma_f32 v[202:203], v[110:111], v[226:227], v[202:203]
	v_pk_fma_f32 v[204:205], v[110:111], v[230:231], v[204:205]
	v_pk_fma_f32 v[206:207], v[110:111], v[234:235], v[206:207]
	ds_read_b128 v[220:223], v156 offset:29696
	ds_read_b128 v[224:227], v156 offset:18432
	ds_read_b128 v[228:231], v156 offset:22528
	ds_read_b128 v[232:235], v156 offset:26624
	v_add_f32_e32 v115, v200, v201
	v_add_f32_e32 v127, v202, v203
	v_add_f32_e32 v129, v204, v205
	v_add_f32_e32 v138, v206, v207
	s_waitcnt lgkmcnt(7)
	v_pk_mul_f32 v[208:209], v[98:99], v[236:237]
	v_pk_mul_f32 v[210:211], v[98:99], v[240:241]
	v_pk_mul_f32 v[190:191], v[98:99], v[244:245]
	v_pk_mul_f32 v[214:215], v[98:99], v[248:249]
	v_pk_fma_f32 v[208:209], v[96:97], v[238:239], v[208:209]
	v_pk_fma_f32 v[210:211], v[96:97], v[242:243], v[210:211]
	v_pk_fma_f32 v[190:191], v[96:97], v[246:247], v[190:191]
	v_pk_fma_f32 v[214:215], v[96:97], v[250:251], v[214:215]
	ds_read_b128 v[236:239], v156 offset:30720
	ds_read_b128 v[240:243], v156 offset:19456
	ds_read_b128 v[244:247], v156 offset:23552
	ds_read_b128 v[248:251], v156 offset:27648
	s_waitcnt lgkmcnt(7)
	v_pk_fma_f32 v[208:209], v[102:103], v[192:193], v[208:209]
	v_pk_fma_f32 v[210:211], v[102:103], v[196:197], v[210:211]
	v_pk_fma_f32 v[190:191], v[102:103], v[216:217], v[190:191]
	v_pk_fma_f32 v[214:215], v[102:103], v[220:221], v[214:215]
	v_pk_fma_f32 v[208:209], v[100:101], v[194:195], v[208:209]
	v_pk_fma_f32 v[210:211], v[100:101], v[198:199], v[210:211]
	v_pk_fma_f32 v[190:191], v[100:101], v[218:219], v[190:191]
	v_pk_fma_f32 v[214:215], v[100:101], v[222:223], v[214:215]
	ds_read_b128 v[192:195], v156 offset:31744
	ds_read_b128 v[196:199], v156 offset:32768
	ds_read_b128 v[216:219], v156 offset:36864
	ds_read_b128 v[220:223], v156 offset:40960
	s_waitcnt lgkmcnt(7)
	v_pk_fma_f32 v[208:209], v[106:107], v[224:225], v[208:209]
	v_pk_fma_f32 v[210:211], v[106:107], v[228:229], v[210:211]
	v_pk_fma_f32 v[190:191], v[106:107], v[232:233], v[190:191]
	v_pk_fma_f32 v[214:215], v[106:107], v[236:237], v[214:215]
	v_pk_fma_f32 v[208:209], v[104:105], v[226:227], v[208:209]
	v_pk_fma_f32 v[210:211], v[104:105], v[230:231], v[210:211]
	v_pk_fma_f32 v[190:191], v[104:105], v[234:235], v[190:191]
	v_pk_fma_f32 v[214:215], v[104:105], v[238:239], v[214:215]
	ds_read_b128 v[224:227], v156 offset:45056
	ds_read_b128 v[228:231], v156 offset:33792
	ds_read_b128 v[232:235], v156 offset:37888
	ds_read_b128 v[236:239], v156 offset:41984
	s_waitcnt lgkmcnt(7)
	v_pk_fma_f32 v[208:209], v[108:109], v[240:241], v[208:209]
	v_pk_fma_f32 v[210:211], v[108:109], v[244:245], v[210:211]
	v_pk_fma_f32 v[190:191], v[108:109], v[248:249], v[190:191]
	v_pk_fma_f32 v[214:215], v[108:109], v[192:193], v[214:215]
	v_pk_fma_f32 v[208:209], v[110:111], v[242:243], v[208:209]
	v_pk_fma_f32 v[210:211], v[110:111], v[246:247], v[210:211]
	v_pk_fma_f32 v[190:191], v[110:111], v[250:251], v[190:191]
	v_pk_fma_f32 v[214:215], v[110:111], v[194:195], v[214:215]
	ds_read_b128 v[240:243], v156 offset:46080
	ds_read_b128 v[244:247], v156 offset:34816
	ds_read_b128 v[248:251], v156 offset:38912
	ds_read_b128 v[192:195], v156 offset:43008
	v_add_f32_e32 v139, v208, v209
	v_add_f32_e32 v148, v210, v211
	v_add_f32_e32 v149, v190, v191
	v_add_f32_e32 v161, v214, v215
	s_waitcnt lgkmcnt(7)
	v_pk_mul_f32 v[200:201], v[98:99], v[196:197]
	v_pk_mul_f32 v[202:203], v[98:99], v[216:217]
	v_pk_mul_f32 v[204:205], v[98:99], v[220:221]
	v_pk_mul_f32 v[206:207], v[98:99], v[224:225]
	v_pk_fma_f32 v[200:201], v[96:97], v[198:199], v[200:201]
	v_pk_fma_f32 v[202:203], v[96:97], v[218:219], v[202:203]
	v_pk_fma_f32 v[204:205], v[96:97], v[222:223], v[204:205]
	v_pk_fma_f32 v[206:207], v[96:97], v[226:227], v[206:207]
	ds_read_b128 v[196:199], v156 offset:47104
	ds_read_b128 v[216:219], v156 offset:35840
	ds_read_b128 v[220:223], v156 offset:39936
	ds_read_b128 v[224:227], v156 offset:44032
	s_waitcnt lgkmcnt(7)
	v_pk_fma_f32 v[200:201], v[102:103], v[228:229], v[200:201]
	v_pk_fma_f32 v[202:203], v[102:103], v[232:233], v[202:203]
	v_pk_fma_f32 v[204:205], v[102:103], v[236:237], v[204:205]
	v_pk_fma_f32 v[206:207], v[102:103], v[240:241], v[206:207]
	v_pk_fma_f32 v[200:201], v[100:101], v[230:231], v[200:201]
	v_pk_fma_f32 v[202:203], v[100:101], v[234:235], v[202:203]
	v_pk_fma_f32 v[204:205], v[100:101], v[238:239], v[204:205]
	v_pk_fma_f32 v[206:207], v[100:101], v[242:243], v[206:207]
	ds_read_b128 v[228:231], v156 offset:48128
	ds_read_b128 v[232:235], v156 offset:49152
	ds_read_b128 v[236:239], v156 offset:53248
	ds_read_b128 v[240:243], v156 offset:57344
	s_waitcnt lgkmcnt(7)
	v_pk_fma_f32 v[200:201], v[106:107], v[244:245], v[200:201]
	v_pk_fma_f32 v[202:203], v[106:107], v[248:249], v[202:203]
	v_pk_fma_f32 v[204:205], v[106:107], v[192:193], v[204:205]
	v_pk_fma_f32 v[206:207], v[106:107], v[196:197], v[206:207]
	v_pk_fma_f32 v[200:201], v[104:105], v[246:247], v[200:201]
	v_pk_fma_f32 v[202:203], v[104:105], v[250:251], v[202:203]
	v_pk_fma_f32 v[204:205], v[104:105], v[194:195], v[204:205]
	v_pk_fma_f32 v[206:207], v[104:105], v[198:199], v[206:207]
	ds_read_b128 v[244:247], v156 offset:61440
	ds_read_b128 v[248:251], v156 offset:50176
	ds_read_b128 v[192:195], v156 offset:54272
	ds_read_b128 v[196:199], v156 offset:58368
	s_waitcnt lgkmcnt(7)
	v_pk_fma_f32 v[200:201], v[108:109], v[216:217], v[200:201]
	v_pk_fma_f32 v[202:203], v[108:109], v[220:221], v[202:203]
	v_pk_fma_f32 v[204:205], v[108:109], v[224:225], v[204:205]
	v_pk_fma_f32 v[206:207], v[108:109], v[228:229], v[206:207]
	v_pk_fma_f32 v[200:201], v[110:111], v[218:219], v[200:201]
	v_pk_fma_f32 v[202:203], v[110:111], v[222:223], v[202:203]
	v_pk_fma_f32 v[204:205], v[110:111], v[226:227], v[204:205]
	v_pk_fma_f32 v[206:207], v[110:111], v[230:231], v[206:207]
	ds_read_b128 v[216:219], v156 offset:62464
	ds_read_b128 v[220:223], v156 offset:51200
	ds_read_b128 v[224:227], v156 offset:55296
	ds_read_b128 v[228:231], v156 offset:59392
	v_add_f32_e32 v170, v200, v201
	v_add_f32_e32 v171, v202, v203
	v_add_f32_e32 v172, v204, v205
	v_add_f32_e32 v173, v206, v207
	s_waitcnt lgkmcnt(7)
	v_pk_mul_f32 v[208:209], v[98:99], v[232:233]
	v_pk_mul_f32 v[210:211], v[98:99], v[236:237]
	v_pk_mul_f32 v[190:191], v[98:99], v[240:241]
	v_pk_mul_f32 v[214:215], v[98:99], v[244:245]
	v_pk_fma_f32 v[208:209], v[96:97], v[234:235], v[208:209]
	v_pk_fma_f32 v[210:211], v[96:97], v[238:239], v[210:211]
	v_pk_fma_f32 v[190:191], v[96:97], v[242:243], v[190:191]
	v_pk_fma_f32 v[214:215], v[96:97], v[246:247], v[214:215]
	ds_read_b128 v[232:235], v156 offset:63488
	ds_read_b128 v[236:239], v156 offset:52224
	ds_read_b128 v[240:243], v156 offset:56320
	ds_read_b128 v[244:247], v156 offset:60416
	s_waitcnt lgkmcnt(7)
	v_pk_fma_f32 v[208:209], v[102:103], v[248:249], v[208:209]
	v_pk_fma_f32 v[210:211], v[102:103], v[192:193], v[210:211]
	v_pk_fma_f32 v[190:191], v[102:103], v[196:197], v[190:191]
	v_pk_fma_f32 v[214:215], v[102:103], v[216:217], v[214:215]
	v_pk_fma_f32 v[208:209], v[100:101], v[250:251], v[208:209]
	v_pk_fma_f32 v[210:211], v[100:101], v[194:195], v[210:211]
	v_pk_fma_f32 v[190:191], v[100:101], v[198:199], v[190:191]
	v_pk_fma_f32 v[214:215], v[100:101], v[218:219], v[214:215]
	ds_read_b128 v[248:251], v156 offset:64512
	s_waitcnt lgkmcnt(4)
	v_pk_fma_f32 v[208:209], v[106:107], v[220:221], v[208:209]
	v_pk_fma_f32 v[210:211], v[106:107], v[224:225], v[210:211]
	v_pk_fma_f32 v[190:191], v[106:107], v[228:229], v[190:191]
	v_pk_fma_f32 v[214:215], v[106:107], v[232:233], v[214:215]
	v_pk_fma_f32 v[208:209], v[104:105], v[222:223], v[208:209]
	v_pk_fma_f32 v[210:211], v[104:105], v[226:227], v[210:211]
	v_pk_fma_f32 v[190:191], v[104:105], v[230:231], v[190:191]
	v_pk_fma_f32 v[214:215], v[104:105], v[234:235], v[214:215]
	s_waitcnt lgkmcnt(0)
	v_pk_fma_f32 v[208:209], v[108:109], v[236:237], v[208:209]
	v_pk_fma_f32 v[210:211], v[108:109], v[240:241], v[210:211]
	v_pk_fma_f32 v[190:191], v[108:109], v[244:245], v[190:191]
	v_pk_fma_f32 v[214:215], v[108:109], v[248:249], v[214:215]
	v_pk_fma_f32 v[208:209], v[110:111], v[238:239], v[208:209]
	v_pk_fma_f32 v[210:211], v[110:111], v[242:243], v[210:211]
	v_pk_fma_f32 v[190:191], v[110:111], v[246:247], v[190:191]
	v_pk_fma_f32 v[214:215], v[110:111], v[250:251], v[214:215]
	v_add_f32_e32 v174, v208, v209
	v_add_f32_e32 v175, v210, v211
	v_add_f32_e32 v176, v190, v191
	v_add_f32_e32 v96, v214, v215
	v_cndmask_b32_e64 v97, v115, v170, s[6:7]
	ds_bpermute_b32 v97, v150, v97
	v_cndmask_b32_e64 v99, v127, v171, s[6:7]
	ds_bpermute_b32 v99, v150, v99
	v_cndmask_b32_e64 v100, v129, v172, s[6:7]
	ds_bpermute_b32 v100, v150, v100
	v_cndmask_b32_e64 v98, v170, v115, s[6:7]
	s_waitcnt lgkmcnt(2)
	v_add_f32_e32 v97, v98, v97
	v_cndmask_b32_e64 v98, v171, v127, s[6:7]
	s_waitcnt lgkmcnt(1)
	v_add_f32_e32 v98, v98, v99
	v_cndmask_b32_e64 v99, v172, v129, s[6:7]
	s_waitcnt lgkmcnt(0)
	v_add_f32_e32 v99, v99, v100
	v_cndmask_b32_e64 v100, v138, v173, s[6:7]
	ds_bpermute_b32 v100, v150, v100
	v_cndmask_b32_e64 v102, v139, v174, s[6:7]
	ds_bpermute_b32 v102, v150, v102
	v_cndmask_b32_e64 v103, v148, v175, s[6:7]
	ds_bpermute_b32 v103, v150, v103
	v_cndmask_b32_e64 v101, v173, v138, s[6:7]
	s_waitcnt lgkmcnt(2)
	v_add_f32_e32 v100, v101, v100
	v_cndmask_b32_e64 v101, v174, v139, s[6:7]
	s_waitcnt lgkmcnt(1)
	v_add_f32_e32 v101, v101, v102
	v_cndmask_b32_e64 v102, v175, v148, s[6:7]
	s_waitcnt lgkmcnt(0)
	v_add_f32_e32 v102, v102, v103
	v_cndmask_b32_e64 v103, v149, v176, s[6:7]
	v_cndmask_b32_e64 v105, v161, v96, s[6:7]
	ds_bpermute_b32 v103, v150, v103
	ds_bpermute_b32 v105, v150, v105
	v_cndmask_b32_e64 v104, v176, v149, s[6:7]
	v_cndmask_b32_e64 v96, v96, v161, s[6:7]
	v_cndmask_b32_e64 v106, v97, v101, s[8:9]
	s_waitcnt lgkmcnt(1)
	v_add_f32_e32 v103, v104, v103
	s_waitcnt lgkmcnt(0)
	v_add_f32_e32 v96, v96, v105
	v_cndmask_b32_e64 v97, v101, v97, s[8:9]
	v_cndmask_b32_e64 v101, v98, v102, s[8:9]
	v_cndmask_b32_e64 v98, v102, v98, s[8:9]
	v_cndmask_b32_e64 v102, v99, v103, s[8:9]
	v_cndmask_b32_e64 v104, v100, v96, s[8:9]
	ds_bpermute_b32 v106, v151, v106
	ds_bpermute_b32 v101, v151, v101
	ds_bpermute_b32 v102, v151, v102
	ds_bpermute_b32 v104, v151, v104
	v_cndmask_b32_e64 v99, v103, v99, s[8:9]
	v_cndmask_b32_e64 v96, v96, v100, s[8:9]
	s_waitcnt lgkmcnt(3)
	v_add_f32_e32 v97, v97, v106
	s_waitcnt lgkmcnt(2)
	v_add_f32_e32 v98, v98, v101
	s_waitcnt lgkmcnt(1)
	v_add_f32_e32 v99, v99, v102
	s_waitcnt lgkmcnt(0)
	v_add_f32_e32 v96, v96, v104
	v_cndmask_b32_e64 v100, v97, v99, s[10:11]
	v_cndmask_b32_e64 v101, v98, v96, s[10:11]
	ds_bpermute_b32 v100, v152, v100
	ds_bpermute_b32 v101, v152, v101
	v_cndmask_b32_e64 v97, v99, v97, s[10:11]
	v_cndmask_b32_e64 v96, v96, v98, s[10:11]
	s_waitcnt lgkmcnt(1)
	v_add_f32_e32 v97, v97, v100
	s_waitcnt lgkmcnt(0)
	v_add_f32_e32 v96, v96, v101
	v_cndmask_b32_e64 v98, v97, v96, s[12:13]
	ds_bpermute_b32 v98, v153, v98
	v_cndmask_b32_e64 v96, v96, v97, s[12:13]
	s_waitcnt lgkmcnt(0)
	v_add_f32_e32 v96, v96, v98
	ds_bpermute_b32 v97, v154, v96
	s_waitcnt lgkmcnt(0)
	v_add_f32_e32 v96, v96, v97
	ds_bpermute_b32 v97, v155, v96
	s_waitcnt lgkmcnt(0)
	v_add_f32_e32 v96, v96, v97
	ds_bpermute_b32 v97, v153, v96
	s_waitcnt lgkmcnt(0)
	v_max_f32_e32 v97, v97, v97
	v_max_f32_e32 v97, v96, v97
	ds_bpermute_b32 v98, v152, v97
	s_waitcnt lgkmcnt(0)
	v_max_f32_e32 v98, v98, v98
	v_max_f32_e32 v97, v97, v98
	ds_bpermute_b32 v98, v151, v97
	s_waitcnt lgkmcnt(0)
	v_max_f32_e32 v98, v98, v98
	v_max_f32_e32 v97, v97, v98
	ds_bpermute_b32 v98, v150, v97
	s_waitcnt lgkmcnt(0)
	v_max_f32_e32 v98, v98, v98
	v_max_f32_e32 v97, v97, v98
	v_sub_f32_e32 v96, v96, v97
	v_mul_f32_e32 v97, 0x3fb8aa3b, v96
	v_fma_f32 v98, v96, s23, -v97
	v_rndne_f32_e32 v99, v97
	v_fmac_f32_e32 v98, 0x32a5705f, v96
	v_sub_f32_e32 v97, v97, v99
	v_add_f32_e32 v97, v97, v98
	v_exp_f32_e32 v97, v97
	v_cvt_i32_f32_e32 v98, v99
	v_cmp_ngt_f32_e32 vcc, s26, v96
	v_ldexp_f32 v97, v97, v98
	s_nop 0
	v_cndmask_b32_e32 v97, 0, v97, vcc
	v_cmp_nlt_f32_e32 vcc, s27, v96
	s_nop 1
	v_cndmask_b32_e32 v96, v160, v97, vcc
	ds_bpermute_b32 v97, v153, v96
	s_waitcnt lgkmcnt(0)
	v_add_f32_e32 v97, v96, v97
	ds_bpermute_b32 v98, v152, v97
	s_waitcnt lgkmcnt(0)
	v_add_f32_e32 v97, v97, v98
	ds_bpermute_b32 v98, v151, v97
	s_waitcnt lgkmcnt(0)
	v_add_f32_e32 v97, v97, v98
	ds_bpermute_b32 v98, v150, v97
	s_and_saveexec_b64 s[24:25], s[14:15]
	s_cbranch_execz .LBB0_679
	s_waitcnt lgkmcnt(0)
	v_add_f32_e32 v97, v97, v98
	v_div_scale_f32 v98, s[28:29], v97, v97, v96
	v_rcp_f32_e32 v99, v98
	v_and_b32_e32 v100, 0xfff, v114
	v_fma_f32 v101, -v98, v99, 1.0
	v_fmac_f32_e32 v99, v101, v99
	v_div_scale_f32 v101, vcc, v96, v97, v96
	v_mul_f32_e32 v102, v101, v99
	v_fma_f32 v103, -v98, v102, v101
	v_fmac_f32_e32 v102, v103, v99
	v_fma_f32 v98, -v98, v102, v101
	v_div_fmas_f32 v98, v98, v99, v102
	v_div_fixup_f32 v98, v98, v97, v96
	v_lshl_or_b32 v96, v112, 4, v157
	v_ashrrev_i32_e32 v97, 31, v96
	v_lshlrev_b64 v[96:97], 14, v[96:97]
	v_lshl_add_u64 v[96:97], s[4:5], 0, v[96:97]
	v_lshlrev_b32_e32 v112, 2, v100
	v_lshl_add_u64 v[96:97], v[96:97], 0, v[112:113]
	global_store_dword v[96:97], v98, off
	s_branch .LBB0_679

.LBB0_1399:
	s_or_b64 exec, exec, s[26:27]
	v_lshlrev_b32_e32 v164, 16, v142
	v_and_b32_e32 v165, 0xffff0000, v142
	v_lshlrev_b32_e32 v162, 16, v144
	v_and_b32_e32 v163, 0xffff0000, v144
	v_pk_mul_f32 v[164:165], v[36:37], v[164:165]
	v_lshlrev_b32_e32 v142, 16, v143
	v_and_b32_e32 v143, 0xffff0000, v143
	v_pk_mul_f32 v[162:163], v[52:53], v[162:163]
	v_pk_fma_f32 v[104:105], v[104:105], s[24:25], v[164:165] op_sel_hi:[1,0,1]
	v_pk_mul_f32 v[142:143], v[38:39], v[142:143]
	v_pk_fma_f32 v[108:109], v[108:109], s[24:25], v[162:163] op_sel_hi:[1,0,1]
	v_and_b32_e32 v163, 0xffff0000, v145
	v_lshlrev_b32_e32 v162, 16, v145
	v_lshlrev_b32_e32 v127, 16, v138
	v_mov_b32_e32 v101, v64
	v_and_b32_e32 v96, 0xffff0000, v140
	v_pk_add_f32 v[164:165], v[104:105], v[104:105] op_sel:[0,1] op_sel_hi:[1,0]
	v_pk_fma_f32 v[106:107], v[106:107], s[24:25], v[142:143] op_sel_hi:[1,0,1]
	v_pk_mul_f32 v[144:145], v[54:55], v[162:163]
	v_pk_mul_f32 v[100:101], v[100:101], v[126:127]
	v_and_b32_e32 v127, 0xffff0000, v138
	v_mul_f32_e32 v163, v77, v96
	v_and_b32_e32 v96, 0xffff0000, v141
	v_pk_add_f32 v[142:143], v[106:107], v[164:165]
	v_lshlrev_b32_e32 v165, 16, v140
	v_lshlrev_b32_e32 v164, 16, v139
	v_and_b32_e32 v138, 0xffff0000, v139
	v_lshlrev_b32_e32 v139, 16, v141
	v_pk_mov_b32 v[140:141], v[66:67], v[78:79] op_sel:[1,0]
	v_pk_fma_f32 v[110:111], v[110:111], s[24:25], v[144:145] op_sel_hi:[1,0,1]
	v_pk_mul_f32 v[138:139], v[140:141], v[138:139]
	v_pk_add_f32 v[140:141], v[106:107], v[142:143] op_sel:[1,0] op_sel_hi:[0,1]
	v_pk_add_f32 v[144:145], v[108:109], v[108:109] op_sel:[0,1] op_sel_hi:[1,0]
	s_waitcnt lgkmcnt(0)
	v_mov_b32_e32 v98, v140
	v_pk_add_f32 v[144:145], v[110:111], v[144:145]
	v_pk_add_f32 v[140:141], v[140:141], s[20:21]
	v_pk_mul_f32 v[98:99], v[98:99], s[2:3]
	v_mov_b32_e32 v149, v65
	v_mul_f32_e32 v96, v79, v96
	v_mov_b32_e32 v141, v99
	v_pk_add_f32 v[98:99], v[110:111], v[144:145] op_sel:[1,0] op_sel_hi:[0,1]
	v_pk_mul_f32 v[148:149], v[148:149], v[126:127]
	v_mov_b32_e32 v99, v96
	v_pk_add_f32 v[98:99], v[140:141], v[98:99]
	v_mov_b32_e32 v140, v100
	v_mov_b32_e32 v141, v148
	v_mov_b32_e32 v148, v101
	v_mov_b32_e32 v166, v66
	v_mov_b32_e32 v167, v76
	v_pk_add_f32 v[100:101], v[140:141], v[148:149]
	v_mul_f32_e32 v97, 0x3fb504f3, v97
	v_pk_mul_f32 v[164:165], v[166:167], v[164:165]
	v_mov_b32_e32 v96, v100
	v_mov_b32_e32 v162, v101
	v_pk_fma_f32 v[102:103], v[102:103], s[24:25], v[164:165] op_sel_hi:[1,0,1]
	v_pk_add_f32 v[96:97], v[96:97], v[162:163]
	v_pk_fma_f32 v[138:139], v[146:147], s[24:25], v[138:139] op_sel_hi:[1,0,1]
	v_pk_add_f32 v[140:141], v[102:103], v[96:97]
	v_mov_b32_e32 v164, v102
	v_pk_add_f32 v[140:141], v[138:139], v[140:141]
	v_mov_b32_e32 v165, v138
	v_pk_add_f32 v[140:141], v[98:99], v[140:141]
	v_ashrrev_i32_e32 v115, 31, v114
	v_add_f32_e32 v96, v140, v141
	ds_bpermute_b32 v98, v150, v96
	s_waitcnt lgkmcnt(0)
	v_add_f32_e32 v96, v96, v98
	ds_bpermute_b32 v98, v151, v96
	s_waitcnt lgkmcnt(0)
	v_add_f32_e32 v96, v96, v98
	ds_bpermute_b32 v98, v152, v96
	s_waitcnt lgkmcnt(0)
	v_add_f32_e32 v96, v96, v98
	ds_bpermute_b32 v98, v153, v96
	s_waitcnt lgkmcnt(0)
	v_add_f32_e32 v96, v96, v98
	ds_bpermute_b32 v98, v154, v96
	s_waitcnt lgkmcnt(0)
	v_add_f32_e32 v96, v96, v98
	ds_bpermute_b32 v98, v155, v96
	s_waitcnt lgkmcnt(0)
	v_add_f32_e32 v96, v96, v98
	v_mul_f32_e32 v140, 0x3a800000, v96
	v_pk_add_f32 v[104:105], v[104:105], v[140:141] op_sel_hi:[1,0] neg_lo:[0,1] neg_hi:[0,1]
	v_pk_add_f32 v[106:107], v[106:107], v[140:141] op_sel_hi:[1,0] neg_lo:[0,1] neg_hi:[0,1]
	v_pk_mul_f32 v[142:143], v[104:105], v[104:105]
	v_pk_mul_f32 v[144:145], v[106:107], v[106:107]
	v_add_f32_e32 v102, v142, v143
	v_pk_add_f32 v[108:109], v[108:109], v[140:141] op_sel_hi:[1,0] neg_lo:[0,1] neg_hi:[0,1]
	v_add_f32_e32 v102, v144, v102
	v_pk_mul_f32 v[148:149], v[108:109], v[108:109]
	v_add_f32_e32 v102, v145, v102
	v_pk_add_f32 v[110:111], v[110:111], v[140:141] op_sel_hi:[1,0] neg_lo:[0,1] neg_hi:[0,1]
	v_add_f32_e32 v102, v148, v102
	v_pk_mul_f32 v[162:163], v[110:111], v[110:111]
	v_add_f32_e32 v102, v149, v102
	v_pk_add_f32 v[146:147], v[100:101], v[140:141] op_sel_hi:[1,0] neg_lo:[0,1] neg_hi:[0,1]
	v_add_f32_e32 v102, v162, v102
	v_pk_mul_f32 v[100:101], v[146:147], v[146:147]
	v_add_f32_e32 v102, v163, v102
	v_pk_add_f32 v[164:165], v[164:165], v[140:141] op_sel_hi:[1,0] neg_lo:[0,1] neg_hi:[0,1]
	v_add_f32_e32 v100, v100, v102
	v_pk_mul_f32 v[166:167], v[164:165], v[164:165]
	v_mov_b32_e32 v96, v103
	v_add_f32_e32 v100, v101, v100
	v_pk_add_f32 v[168:169], v[96:97], v[140:141] op_sel_hi:[1,0] neg_lo:[0,1] neg_hi:[0,1]
	v_add_f32_e32 v100, v166, v100
	v_pk_mul_f32 v[96:97], v[168:169], v[168:169]
	v_mov_b32_e32 v98, v139
	v_add_f32_e32 v100, v167, v100
	v_pk_add_f32 v[138:139], v[98:99], v[140:141] op_sel_hi:[1,0] neg_lo:[0,1] neg_hi:[0,1]
	v_add_f32_e32 v96, v96, v100
	v_pk_mul_f32 v[98:99], v[138:139], v[138:139]
	v_add_f32_e32 v96, v97, v96
	v_add_f32_e32 v96, v98, v96
	v_add_f32_e32 v96, v99, v96
	ds_bpermute_b32 v97, v150, v96
	v_pk_add_f32 v[102:103], v[34:35], 1.0 op_sel_hi:[1,0]
	v_pk_add_f32 v[144:145], v[40:41], 1.0 op_sel_hi:[1,0]
	v_pk_add_f32 v[148:149], v[42:43], 1.0 op_sel_hi:[1,0]
	v_pk_add_f32 v[162:163], v[56:57], 1.0 op_sel_hi:[1,0]
	s_waitcnt lgkmcnt(0)
	v_add_f32_e32 v96, v96, v97
	ds_bpermute_b32 v97, v151, v96
	v_pk_add_f32 v[166:167], v[58:59], 1.0 op_sel_hi:[1,0]
	s_waitcnt lgkmcnt(0)
	v_add_f32_e32 v96, v96, v97
	ds_bpermute_b32 v97, v152, v96
	s_waitcnt lgkmcnt(0)
	v_add_f32_e32 v96, v96, v97
	ds_bpermute_b32 v97, v153, v96
	s_waitcnt lgkmcnt(0)
	v_add_f32_e32 v98, v96, v97
	ds_bpermute_b32 v99, v154, v98
	v_lshlrev_b64 v[96:97], 12, v[114:115]
	v_lshl_add_u64 v[140:141], v[122:123], 0, v[96:97]
	v_pk_add_f32 v[96:97], v[32:33], 1.0 op_sel_hi:[1,0]
	s_waitcnt lgkmcnt(0)
	v_add_f32_e32 v100, v98, v99
	ds_bpermute_b32 v101, v155, v100
	v_lshlrev_b64 v[98:99], 11, v[114:115]
	v_lshl_add_u64 v[142:143], v[124:125], 0, v[98:99]
	s_waitcnt lgkmcnt(0)
	v_add_f32_e32 v98, v100, v101
	v_fmamk_f32 v98, v98, 0x3a800000, v159
	v_mul_f32_e32 v99, 0x4b800000, v98
	v_cmp_gt_f32_e32 vcc, s21, v98
	s_nop 1
	v_cndmask_b32_e32 v98, v98, v99, vcc
	v_rsq_f32_e32 v98, v98
	s_nop 0
	v_mul_f32_e32 v99, 0x45800000, v98
	v_cndmask_b32_e32 v170, v98, v99, vcc
	v_pk_mul_f32 v[98:99], v[104:105], v[170:171] op_sel_hi:[1,0]
	v_pk_mul_f32 v[100:101], v[106:107], v[170:171] op_sel_hi:[1,0]
	v_pk_fma_f32 v[98:99], v[28:29], v[98:99], v[24:25]
	v_pk_fma_f32 v[100:101], v[30:31], v[100:101], v[26:27]
	global_store_dwordx4 v[140:141], v[98:101], off sc1 nt
	s_nop 1
	v_pk_fma_f32 v[98:99], v[96:97], v[98:99], v[44:45]
	v_pk_fma_f32 v[96:97], v[102:103], v[100:101], v[46:47]
	v_cvt_pk_bf16_f32 v100, v98, v99
	v_cvt_pk_bf16_f32 v101, v96, v97
	global_store_dwordx2 v[142:143], v[100:101], off
	v_pk_mul_f32 v[100:101], v[108:109], v[170:171] op_sel_hi:[1,0]
	s_nop 0
	v_pk_fma_f32 v[102:103], v[20:21], v[100:101], v[12:13]
	v_pk_mul_f32 v[100:101], v[110:111], v[170:171] op_sel_hi:[1,0]
	v_pk_mul_f32 v[110:111], v[138:139], v[170:171] op_sel_hi:[1,0]
	v_pk_fma_f32 v[104:105], v[22:23], v[100:101], v[14:15]
	global_store_dwordx4 v[140:141], v[102:105], off offset:1024 sc1 nt
	v_pk_fma_f32 v[100:101], v[148:149], v[104:105], v[50:51]
	v_pk_fma_f32 v[110:111], v[6:7], v[110:111], v[2:3]
	v_pk_fma_f32 v[102:103], v[144:145], v[102:103], v[48:49]
	v_cvt_pk_bf16_f32 v105, v100, v101
	v_cvt_pk_bf16_f32 v104, v102, v103
	global_store_dwordx2 v[142:143], v[104:105], off offset:512
	v_pk_mul_f32 v[104:105], v[146:147], v[170:171] op_sel_hi:[1,0]
	v_pk_add_f32 v[138:139], v[68:69], 1.0 op_sel_hi:[1,0]
	v_pk_fma_f32 v[106:107], v[16:17], v[104:105], v[8:9]
	v_pk_mul_f32 v[104:105], v[164:165], v[170:171] op_sel_hi:[1,0]
	s_nop 0
	v_pk_fma_f32 v[108:109], v[18:19], v[104:105], v[10:11]
	global_store_dwordx4 v[140:141], v[106:109], off offset:2048 sc1 nt
	v_pk_fma_f32 v[104:105], v[166:167], v[108:109], v[62:63]
	s_nop 0
	v_pk_fma_f32 v[106:107], v[162:163], v[106:107], v[60:61]
	v_cvt_pk_bf16_f32 v109, v104, v105
	v_cvt_pk_bf16_f32 v108, v106, v107
	global_store_dwordx2 v[142:143], v[108:109], off offset:1024
	v_pk_mul_f32 v[108:109], v[168:169], v[170:171] op_sel_hi:[1,0]
	s_nop 0
	v_pk_fma_f32 v[108:109], v[4:5], v[108:109], v[0:1]
	global_store_dwordx4 v[140:141], v[108:111], off offset:3072 sc1 nt
	s_nop 1
	v_pk_fma_f32 v[108:109], v[138:139], v[108:109], v[72:73]
	v_pk_add_f32 v[138:139], v[70:71], 1.0 op_sel_hi:[1,0]
	v_cvt_pk_bf16_f32 v144, v108, v109
	v_pk_fma_f32 v[110:111], v[138:139], v[110:111], v[74:75]
	v_cvt_pk_bf16_f32 v145, v110, v111
	global_store_dwordx2 v[142:143], v[144:145], off offset:1536
	ds_read_b128 v[216:219], v156
	ds_read_b128 v[220:223], v156 offset:4096
	ds_read_b128 v[224:227], v156 offset:8192
	ds_read_b128 v[228:231], v156 offset:12288
	ds_read_b128 v[232:235], v156 offset:1024
	ds_read_b128 v[236:239], v156 offset:5120
	ds_read_b128 v[240:243], v156 offset:9216
	ds_read_b128 v[244:247], v156 offset:13312
	ds_read_b128 v[248:251], v156 offset:2048
	ds_read_b128 v[192:195], v156 offset:6144
	ds_read_b128 v[196:199], v156 offset:10240
	s_waitcnt lgkmcnt(7)
	v_pk_mul_f32 v[200:201], v[98:99], v[216:217]
	v_pk_mul_f32 v[202:203], v[98:99], v[220:221]
	v_pk_mul_f32 v[204:205], v[98:99], v[224:225]
	v_pk_mul_f32 v[206:207], v[98:99], v[228:229]
	v_pk_fma_f32 v[200:201], v[96:97], v[218:219], v[200:201]
	v_pk_fma_f32 v[202:203], v[96:97], v[222:223], v[202:203]
	v_pk_fma_f32 v[204:205], v[96:97], v[226:227], v[204:205]
	v_pk_fma_f32 v[206:207], v[96:97], v[230:231], v[206:207]
	ds_read_b128 v[216:219], v156 offset:14336
	ds_read_b128 v[220:223], v156 offset:3072
	ds_read_b128 v[224:227], v156 offset:7168
	ds_read_b128 v[228:231], v156 offset:11264
	s_waitcnt lgkmcnt(7)
	v_pk_fma_f32 v[200:201], v[102:103], v[232:233], v[200:201]
	v_pk_fma_f32 v[202:203], v[102:103], v[236:237], v[202:203]
	v_pk_fma_f32 v[204:205], v[102:103], v[240:241], v[204:205]
	v_pk_fma_f32 v[206:207], v[102:103], v[244:245], v[206:207]
	v_pk_fma_f32 v[200:201], v[100:101], v[234:235], v[200:201]
	v_pk_fma_f32 v[202:203], v[100:101], v[238:239], v[202:203]
	v_pk_fma_f32 v[204:205], v[100:101], v[242:243], v[204:205]
	v_pk_fma_f32 v[206:207], v[100:101], v[246:247], v[206:207]
	ds_read_b128 v[232:235], v156 offset:15360
	ds_read_b128 v[236:239], v156 offset:16384
	ds_read_b128 v[240:243], v156 offset:20480
	ds_read_b128 v[244:247], v156 offset:24576
	s_waitcnt lgkmcnt(7)
	v_pk_fma_f32 v[200:201], v[106:107], v[248:249], v[200:201]
	v_pk_fma_f32 v[202:203], v[106:107], v[192:193], v[202:203]
	v_pk_fma_f32 v[204:205], v[106:107], v[196:197], v[204:205]
	v_pk_fma_f32 v[206:207], v[106:107], v[216:217], v[206:207]
	v_pk_fma_f32 v[200:201], v[104:105], v[250:251], v[200:201]
	v_pk_fma_f32 v[202:203], v[104:105], v[194:195], v[202:203]
	v_pk_fma_f32 v[204:205], v[104:105], v[198:199], v[204:205]
	v_pk_fma_f32 v[206:207], v[104:105], v[218:219], v[206:207]
	ds_read_b128 v[248:251], v156 offset:28672
	ds_read_b128 v[192:195], v156 offset:17408
	ds_read_b128 v[196:199], v156 offset:21504
	ds_read_b128 v[216:219], v156 offset:25600
	s_waitcnt lgkmcnt(7)
	v_pk_fma_f32 v[200:201], v[108:109], v[220:221], v[200:201]
	v_pk_fma_f32 v[202:203], v[108:109], v[224:225], v[202:203]
	v_pk_fma_f32 v[204:205], v[108:109], v[228:229], v[204:205]
	v_pk_fma_f32 v[206:207], v[108:109], v[232:233], v[206:207]
	v_pk_fma_f32 v[200:201], v[110:111], v[222:223], v[200:201]
	v_pk_fma_f32 v[202:203], v[110:111], v[226:227], v[202:203]
	v_pk_fma_f32 v[204:205], v[110:111], v[230:231], v[204:205]
	v_pk_fma_f32 v[206:207], v[110:111], v[234:235], v[206:207]
	ds_read_b128 v[220:223], v156 offset:29696
	ds_read_b128 v[224:227], v156 offset:18432
	ds_read_b128 v[228:231], v156 offset:22528
	ds_read_b128 v[232:235], v156 offset:26624
	v_add_f32_e32 v115, v200, v201
	v_add_f32_e32 v127, v202, v203
	v_add_f32_e32 v129, v204, v205
	v_add_f32_e32 v138, v206, v207
	s_waitcnt lgkmcnt(7)
	v_pk_mul_f32 v[208:209], v[98:99], v[236:237]
	v_pk_mul_f32 v[210:211], v[98:99], v[240:241]
	v_pk_mul_f32 v[190:191], v[98:99], v[244:245]
	v_pk_mul_f32 v[214:215], v[98:99], v[248:249]
	v_pk_fma_f32 v[208:209], v[96:97], v[238:239], v[208:209]
	v_pk_fma_f32 v[210:211], v[96:97], v[242:243], v[210:211]
	v_pk_fma_f32 v[190:191], v[96:97], v[246:247], v[190:191]
	v_pk_fma_f32 v[214:215], v[96:97], v[250:251], v[214:215]
	ds_read_b128 v[236:239], v156 offset:30720
	ds_read_b128 v[240:243], v156 offset:19456
	ds_read_b128 v[244:247], v156 offset:23552
	ds_read_b128 v[248:251], v156 offset:27648
	s_waitcnt lgkmcnt(7)
	v_pk_fma_f32 v[208:209], v[102:103], v[192:193], v[208:209]
	v_pk_fma_f32 v[210:211], v[102:103], v[196:197], v[210:211]
	v_pk_fma_f32 v[190:191], v[102:103], v[216:217], v[190:191]
	v_pk_fma_f32 v[214:215], v[102:103], v[220:221], v[214:215]
	v_pk_fma_f32 v[208:209], v[100:101], v[194:195], v[208:209]
	v_pk_fma_f32 v[210:211], v[100:101], v[198:199], v[210:211]
	v_pk_fma_f32 v[190:191], v[100:101], v[218:219], v[190:191]
	v_pk_fma_f32 v[214:215], v[100:101], v[222:223], v[214:215]
	ds_read_b128 v[192:195], v156 offset:31744
	ds_read_b128 v[196:199], v156 offset:32768
	ds_read_b128 v[216:219], v156 offset:36864
	ds_read_b128 v[220:223], v156 offset:40960
	s_waitcnt lgkmcnt(7)
	v_pk_fma_f32 v[208:209], v[106:107], v[224:225], v[208:209]
	v_pk_fma_f32 v[210:211], v[106:107], v[228:229], v[210:211]
	v_pk_fma_f32 v[190:191], v[106:107], v[232:233], v[190:191]
	v_pk_fma_f32 v[214:215], v[106:107], v[236:237], v[214:215]
	v_pk_fma_f32 v[208:209], v[104:105], v[226:227], v[208:209]
	v_pk_fma_f32 v[210:211], v[104:105], v[230:231], v[210:211]
	v_pk_fma_f32 v[190:191], v[104:105], v[234:235], v[190:191]
	v_pk_fma_f32 v[214:215], v[104:105], v[238:239], v[214:215]
	ds_read_b128 v[224:227], v156 offset:45056
	ds_read_b128 v[228:231], v156 offset:33792
	ds_read_b128 v[232:235], v156 offset:37888
	ds_read_b128 v[236:239], v156 offset:41984
	s_waitcnt lgkmcnt(7)
	v_pk_fma_f32 v[208:209], v[108:109], v[240:241], v[208:209]
	v_pk_fma_f32 v[210:211], v[108:109], v[244:245], v[210:211]
	v_pk_fma_f32 v[190:191], v[108:109], v[248:249], v[190:191]
	v_pk_fma_f32 v[214:215], v[108:109], v[192:193], v[214:215]
	v_pk_fma_f32 v[208:209], v[110:111], v[242:243], v[208:209]
	v_pk_fma_f32 v[210:211], v[110:111], v[246:247], v[210:211]
	v_pk_fma_f32 v[190:191], v[110:111], v[250:251], v[190:191]
	v_pk_fma_f32 v[214:215], v[110:111], v[194:195], v[214:215]
	ds_read_b128 v[240:243], v156 offset:46080
	ds_read_b128 v[244:247], v156 offset:34816
	ds_read_b128 v[248:251], v156 offset:38912
	ds_read_b128 v[192:195], v156 offset:43008
	v_add_f32_e32 v139, v208, v209
	v_add_f32_e32 v148, v210, v211
	v_add_f32_e32 v149, v190, v191
	v_add_f32_e32 v161, v214, v215
	s_waitcnt lgkmcnt(7)
	v_pk_mul_f32 v[200:201], v[98:99], v[196:197]
	v_pk_mul_f32 v[202:203], v[98:99], v[216:217]
	v_pk_mul_f32 v[204:205], v[98:99], v[220:221]
	v_pk_mul_f32 v[206:207], v[98:99], v[224:225]
	v_pk_fma_f32 v[200:201], v[96:97], v[198:199], v[200:201]
	v_pk_fma_f32 v[202:203], v[96:97], v[218:219], v[202:203]
	v_pk_fma_f32 v[204:205], v[96:97], v[222:223], v[204:205]
	v_pk_fma_f32 v[206:207], v[96:97], v[226:227], v[206:207]
	ds_read_b128 v[196:199], v156 offset:47104
	ds_read_b128 v[216:219], v156 offset:35840
	ds_read_b128 v[220:223], v156 offset:39936
	ds_read_b128 v[224:227], v156 offset:44032
	s_waitcnt lgkmcnt(7)
	v_pk_fma_f32 v[200:201], v[102:103], v[228:229], v[200:201]
	v_pk_fma_f32 v[202:203], v[102:103], v[232:233], v[202:203]
	v_pk_fma_f32 v[204:205], v[102:103], v[236:237], v[204:205]
	v_pk_fma_f32 v[206:207], v[102:103], v[240:241], v[206:207]
	v_pk_fma_f32 v[200:201], v[100:101], v[230:231], v[200:201]
	v_pk_fma_f32 v[202:203], v[100:101], v[234:235], v[202:203]
	v_pk_fma_f32 v[204:205], v[100:101], v[238:239], v[204:205]
	v_pk_fma_f32 v[206:207], v[100:101], v[242:243], v[206:207]
	ds_read_b128 v[228:231], v156 offset:48128
	ds_read_b128 v[232:235], v156 offset:49152
	ds_read_b128 v[236:239], v156 offset:53248
	ds_read_b128 v[240:243], v156 offset:57344
	s_waitcnt lgkmcnt(7)
	v_pk_fma_f32 v[200:201], v[106:107], v[244:245], v[200:201]
	v_pk_fma_f32 v[202:203], v[106:107], v[248:249], v[202:203]
	v_pk_fma_f32 v[204:205], v[106:107], v[192:193], v[204:205]
	v_pk_fma_f32 v[206:207], v[106:107], v[196:197], v[206:207]
	v_pk_fma_f32 v[200:201], v[104:105], v[246:247], v[200:201]
	v_pk_fma_f32 v[202:203], v[104:105], v[250:251], v[202:203]
	v_pk_fma_f32 v[204:205], v[104:105], v[194:195], v[204:205]
	v_pk_fma_f32 v[206:207], v[104:105], v[198:199], v[206:207]
	ds_read_b128 v[244:247], v156 offset:61440
	ds_read_b128 v[248:251], v156 offset:50176
	ds_read_b128 v[192:195], v156 offset:54272
	ds_read_b128 v[196:199], v156 offset:58368
	s_waitcnt lgkmcnt(7)
	v_pk_fma_f32 v[200:201], v[108:109], v[216:217], v[200:201]
	v_pk_fma_f32 v[202:203], v[108:109], v[220:221], v[202:203]
	v_pk_fma_f32 v[204:205], v[108:109], v[224:225], v[204:205]
	v_pk_fma_f32 v[206:207], v[108:109], v[228:229], v[206:207]
	v_pk_fma_f32 v[200:201], v[110:111], v[218:219], v[200:201]
	v_pk_fma_f32 v[202:203], v[110:111], v[222:223], v[202:203]
	v_pk_fma_f32 v[204:205], v[110:111], v[226:227], v[204:205]
	v_pk_fma_f32 v[206:207], v[110:111], v[230:231], v[206:207]
	ds_read_b128 v[216:219], v156 offset:62464
	ds_read_b128 v[220:223], v156 offset:51200
	ds_read_b128 v[224:227], v156 offset:55296
	ds_read_b128 v[228:231], v156 offset:59392
	v_add_f32_e32 v170, v200, v201
	v_add_f32_e32 v171, v202, v203
	v_add_f32_e32 v172, v204, v205
	v_add_f32_e32 v173, v206, v207
	s_waitcnt lgkmcnt(7)
	v_pk_mul_f32 v[208:209], v[98:99], v[232:233]
	v_pk_mul_f32 v[210:211], v[98:99], v[236:237]
	v_pk_mul_f32 v[190:191], v[98:99], v[240:241]
	v_pk_mul_f32 v[214:215], v[98:99], v[244:245]
	v_pk_fma_f32 v[208:209], v[96:97], v[234:235], v[208:209]
	v_pk_fma_f32 v[210:211], v[96:97], v[238:239], v[210:211]
	v_pk_fma_f32 v[190:191], v[96:97], v[242:243], v[190:191]
	v_pk_fma_f32 v[214:215], v[96:97], v[246:247], v[214:215]
	ds_read_b128 v[232:235], v156 offset:63488
	ds_read_b128 v[236:239], v156 offset:52224
	ds_read_b128 v[240:243], v156 offset:56320
	ds_read_b128 v[244:247], v156 offset:60416
	s_waitcnt lgkmcnt(7)
	v_pk_fma_f32 v[208:209], v[102:103], v[248:249], v[208:209]
	v_pk_fma_f32 v[210:211], v[102:103], v[192:193], v[210:211]
	v_pk_fma_f32 v[190:191], v[102:103], v[196:197], v[190:191]
	v_pk_fma_f32 v[214:215], v[102:103], v[216:217], v[214:215]
	v_pk_fma_f32 v[208:209], v[100:101], v[250:251], v[208:209]
	v_pk_fma_f32 v[210:211], v[100:101], v[194:195], v[210:211]
	v_pk_fma_f32 v[190:191], v[100:101], v[198:199], v[190:191]
	v_pk_fma_f32 v[214:215], v[100:101], v[218:219], v[214:215]
	ds_read_b128 v[248:251], v156 offset:64512
	s_waitcnt lgkmcnt(4)
	v_pk_fma_f32 v[208:209], v[106:107], v[220:221], v[208:209]
	v_pk_fma_f32 v[210:211], v[106:107], v[224:225], v[210:211]
	v_pk_fma_f32 v[190:191], v[106:107], v[228:229], v[190:191]
	v_pk_fma_f32 v[214:215], v[106:107], v[232:233], v[214:215]
	v_pk_fma_f32 v[208:209], v[104:105], v[222:223], v[208:209]
	v_pk_fma_f32 v[210:211], v[104:105], v[226:227], v[210:211]
	v_pk_fma_f32 v[190:191], v[104:105], v[230:231], v[190:191]
	v_pk_fma_f32 v[214:215], v[104:105], v[234:235], v[214:215]
	s_waitcnt lgkmcnt(0)
	v_pk_fma_f32 v[208:209], v[108:109], v[236:237], v[208:209]
	v_pk_fma_f32 v[210:211], v[108:109], v[240:241], v[210:211]
	v_pk_fma_f32 v[190:191], v[108:109], v[244:245], v[190:191]
	v_pk_fma_f32 v[214:215], v[108:109], v[248:249], v[214:215]
	v_pk_fma_f32 v[208:209], v[110:111], v[238:239], v[208:209]
	v_pk_fma_f32 v[210:211], v[110:111], v[242:243], v[210:211]
	v_pk_fma_f32 v[190:191], v[110:111], v[246:247], v[190:191]
	v_pk_fma_f32 v[214:215], v[110:111], v[250:251], v[214:215]
	v_add_f32_e32 v174, v208, v209
	v_add_f32_e32 v175, v210, v211
	v_add_f32_e32 v176, v190, v191
	v_add_f32_e32 v96, v214, v215
	v_cndmask_b32_e64 v97, v115, v170, s[6:7]
	ds_bpermute_b32 v97, v150, v97
	v_cndmask_b32_e64 v99, v127, v171, s[6:7]
	ds_bpermute_b32 v99, v150, v99
	v_cndmask_b32_e64 v100, v129, v172, s[6:7]
	ds_bpermute_b32 v100, v150, v100
	v_cndmask_b32_e64 v98, v170, v115, s[6:7]
	s_waitcnt lgkmcnt(2)
	v_add_f32_e32 v97, v98, v97
	v_cndmask_b32_e64 v98, v171, v127, s[6:7]
	s_waitcnt lgkmcnt(1)
	v_add_f32_e32 v98, v98, v99
	v_cndmask_b32_e64 v99, v172, v129, s[6:7]
	s_waitcnt lgkmcnt(0)
	v_add_f32_e32 v99, v99, v100
	v_cndmask_b32_e64 v100, v138, v173, s[6:7]
	ds_bpermute_b32 v100, v150, v100
	v_cndmask_b32_e64 v102, v139, v174, s[6:7]
	ds_bpermute_b32 v102, v150, v102
	v_cndmask_b32_e64 v103, v148, v175, s[6:7]
	ds_bpermute_b32 v103, v150, v103
	v_cndmask_b32_e64 v101, v173, v138, s[6:7]
	s_waitcnt lgkmcnt(2)
	v_add_f32_e32 v100, v101, v100
	v_cndmask_b32_e64 v101, v174, v139, s[6:7]
	s_waitcnt lgkmcnt(1)
	v_add_f32_e32 v101, v101, v102
	v_cndmask_b32_e64 v102, v175, v148, s[6:7]
	s_waitcnt lgkmcnt(0)
	v_add_f32_e32 v102, v102, v103
	v_cndmask_b32_e64 v103, v149, v176, s[6:7]
	v_cndmask_b32_e64 v105, v161, v96, s[6:7]
	ds_bpermute_b32 v103, v150, v103
	ds_bpermute_b32 v105, v150, v105
	v_cndmask_b32_e64 v104, v176, v149, s[6:7]
	v_cndmask_b32_e64 v96, v96, v161, s[6:7]
	v_cndmask_b32_e64 v106, v97, v101, s[8:9]
	s_waitcnt lgkmcnt(1)
	v_add_f32_e32 v103, v104, v103
	s_waitcnt lgkmcnt(0)
	v_add_f32_e32 v96, v96, v105
	v_cndmask_b32_e64 v97, v101, v97, s[8:9]
	v_cndmask_b32_e64 v101, v98, v102, s[8:9]
	v_cndmask_b32_e64 v98, v102, v98, s[8:9]
	v_cndmask_b32_e64 v102, v99, v103, s[8:9]
	v_cndmask_b32_e64 v104, v100, v96, s[8:9]
	ds_bpermute_b32 v106, v151, v106
	ds_bpermute_b32 v101, v151, v101
	ds_bpermute_b32 v102, v151, v102
	ds_bpermute_b32 v104, v151, v104
	v_cndmask_b32_e64 v99, v103, v99, s[8:9]
	v_cndmask_b32_e64 v96, v96, v100, s[8:9]
	s_waitcnt lgkmcnt(3)
	v_add_f32_e32 v97, v97, v106
	s_waitcnt lgkmcnt(2)
	v_add_f32_e32 v98, v98, v101
	s_waitcnt lgkmcnt(1)
	v_add_f32_e32 v99, v99, v102
	s_waitcnt lgkmcnt(0)
	v_add_f32_e32 v96, v96, v104
	v_cndmask_b32_e64 v100, v97, v99, s[10:11]
	v_cndmask_b32_e64 v101, v98, v96, s[10:11]
	ds_bpermute_b32 v100, v152, v100
	ds_bpermute_b32 v101, v152, v101
	v_cndmask_b32_e64 v97, v99, v97, s[10:11]
	v_cndmask_b32_e64 v96, v96, v98, s[10:11]
	s_waitcnt lgkmcnt(1)
	v_add_f32_e32 v97, v97, v100
	s_waitcnt lgkmcnt(0)
	v_add_f32_e32 v96, v96, v101
	v_cndmask_b32_e64 v98, v97, v96, s[12:13]
	ds_bpermute_b32 v98, v153, v98
	v_cndmask_b32_e64 v96, v96, v97, s[12:13]
	s_waitcnt lgkmcnt(0)
	v_add_f32_e32 v96, v96, v98
	ds_bpermute_b32 v97, v154, v96
	s_waitcnt lgkmcnt(0)
	v_add_f32_e32 v96, v96, v97
	ds_bpermute_b32 v97, v155, v96
	s_waitcnt lgkmcnt(0)
	v_add_f32_e32 v96, v96, v97
	ds_bpermute_b32 v97, v153, v96
	s_waitcnt lgkmcnt(0)
	v_max_f32_e32 v97, v97, v97
	v_max_f32_e32 v97, v96, v97
	ds_bpermute_b32 v98, v152, v97
	s_waitcnt lgkmcnt(0)
	v_max_f32_e32 v98, v98, v98
	v_max_f32_e32 v97, v97, v98
	ds_bpermute_b32 v98, v151, v97
	s_waitcnt lgkmcnt(0)
	v_max_f32_e32 v98, v98, v98
	v_max_f32_e32 v97, v97, v98
	ds_bpermute_b32 v98, v150, v97
	s_waitcnt lgkmcnt(0)
	v_max_f32_e32 v98, v98, v98
	v_max_f32_e32 v97, v97, v98
	v_sub_f32_e32 v96, v96, v97
	v_mul_f32_e32 v97, 0x3fb8aa3b, v96
	v_fma_f32 v98, v96, s25, -v97
	v_rndne_f32_e32 v99, v97
	v_fmac_f32_e32 v98, 0x32a5705f, v96
	v_sub_f32_e32 v97, v97, v99
	v_add_f32_e32 v97, v97, v98
	v_exp_f32_e32 v97, v97
	v_cvt_i32_f32_e32 v98, v99
	v_cmp_ngt_f32_e32 vcc, s28, v96
	v_ldexp_f32 v97, v97, v98
	s_nop 0
	v_cndmask_b32_e32 v97, 0, v97, vcc
	v_cmp_nlt_f32_e32 vcc, s29, v96
	s_nop 1
	v_cndmask_b32_e32 v96, v160, v97, vcc
	ds_bpermute_b32 v97, v153, v96
	s_waitcnt lgkmcnt(0)
	v_add_f32_e32 v97, v96, v97
	ds_bpermute_b32 v98, v152, v97
	s_waitcnt lgkmcnt(0)
	v_add_f32_e32 v97, v97, v98
	ds_bpermute_b32 v98, v151, v97
	s_waitcnt lgkmcnt(0)
	v_add_f32_e32 v97, v97, v98
	ds_bpermute_b32 v98, v150, v97
	s_and_saveexec_b64 s[26:27], s[14:15]
	s_cbranch_execz .LBB0_1394
	s_waitcnt lgkmcnt(0)
	v_add_f32_e32 v97, v97, v98
	v_div_scale_f32 v98, s[30:31], v97, v97, v96
	v_rcp_f32_e32 v99, v98
	v_and_b32_e32 v100, 0xfff, v114
	v_fma_f32 v101, -v98, v99, 1.0
	v_fmac_f32_e32 v99, v101, v99
	v_div_scale_f32 v101, vcc, v96, v97, v96
	v_mul_f32_e32 v102, v101, v99
	v_fma_f32 v103, -v98, v102, v101
	v_fmac_f32_e32 v102, v103, v99
	v_fma_f32 v98, -v98, v102, v101
	v_div_fmas_f32 v98, v98, v99, v102
	v_div_fixup_f32 v98, v98, v97, v96
	v_lshl_or_b32 v96, v112, 4, v157
	v_ashrrev_i32_e32 v97, 31, v96
	v_lshlrev_b64 v[96:97], 14, v[96:97]
	v_lshl_add_u64 v[96:97], s[18:19], 0, v[96:97]
	v_lshlrev_b32_e32 v112, 2, v100
	v_lshl_add_u64 v[96:97], v[96:97], 0, v[112:113]
	global_store_dword v[96:97], v98, off
	s_branch .LBB0_1394
